# FFN1 k-loop: two k-tiles in flight instead of three (prologue requests 2 tiles, in-loop request is tile kt+2, wait vmcnt(5)); other loops unchanged
# baseline (speedup 1.0000x reference)
; #define G3_TILE(kt_, st_) do { const size_t ko_ = (size_t)(kt_) * 1024; unsigned char* d_ = smem + (st_) * 20480; \
;         _Pragma("unroll") for (int s_ = 0; s_ < 12; ++s_) GLDS16(Abase + (size_t)s_ * ksub + ko_ + voff, d_ + s_ * 1024); \
;         _Pragma("unroll") for (int s_ = 0; s_ < 8; ++s_) GLDS16(Bbase + (size_t)s_ * ksub + ko_ + voff, d_ + 12288 + s_ * 1024); } while (0)
; template <int EPI>
; __device__ __forceinline__ void gemm_tile3(const Params& p, int l, const u16* __restrict__ A, int lda, const u16* __restrict__ Bt, int K, int m0, int n0, unsigned char* smem) {
;     ...
;     const int nk = K >> 5;
;     if (wid < 3) G3_TILE(wid, wid);
;     const unsigned char* fa = smem + (wr * 6) * 1024 + fr * 64 + fq * 16;
;     const unsigned char* fb = smem + 12288 + (wc * 4) * 1024 + fr * 64 + fq * 16;
;     int st = 0, stn = 3;
.LoA_pro:
	s_add_i32 s17, s16, s54
	s_add_i32 s18, s16, s55
	s_mov_b32 m0, s17
	s_add_i32 s17, s17, 0x400
	global_load_lds_dwordx4 v252, s[28:29]
	s_mov_b32 m0, s17
	s_add_i32 s17, s17, 0x400
	global_load_lds_dwordx4 v253, s[28:29]
	s_mov_b32 m0, s17
	s_nop 0
	global_load_lds_dwordx4 v254, s[28:29]
	s_mov_b32 m0, s18
	s_add_i32 s18, s18, 0x400
	global_load_lds_dwordx4 v252, s[30:31]
	s_mov_b32 m0, s18
	s_add_u32 s28, s28, 0x400
	global_load_lds_dwordx4 v253, s[30:31]
	s_addc_u32 s29, s29, 0
	s_add_u32 s30, s30, 0x400
	s_addc_u32 s31, s31, 0
	s_add_i32 s16, s16, 0x5000
	s_cmp_lg_u32 s16, 0xa000
	s_cbranch_scc1 .LoA_pro
	v_ashrrev_i32_e32 v105, 7, v104
	s_movk_i32 s17, 0x1800
	v_and_b32_e32 v106, 15, v104
	v_mul_lo_u32 v2, v105, s17
	v_and_b32_e32 v99, 1, v98
	v_lshlrev_b32_e32 v3, 6, v106
	v_and_b32_e32 v4, 48, v104
	v_and_b32_e32 v5, 8, v104
	v_lshlrev_b32_e32 v5, 2, v5
	v_xor_b32_e32 v4, v4, v5
	v_add3_u32 v107, v2, v3, v4
	v_lshlrev_b32_e32 v2, 12, v99
	v_add3_u32 v108, v2, v3, v4
	s_waitcnt lgkmcnt(0)
	v_mov_b32_e32 v2, 0
	v_mov_b32_e32 v3, v2
	v_mov_b32_e32 v4, v2
	v_mov_b32_e32 v5, v2
	v_mov_b32_e32 v6, v2
	v_mov_b32_e32 v7, v2
	v_mov_b32_e32 v8, v2
	v_mov_b32_e32 v9, v2
	v_mov_b32_e32 v10, v2
	v_mov_b32_e32 v11, v2
	v_mov_b32_e32 v12, v2
	v_mov_b32_e32 v13, v2
	v_mov_b32_e32 v14, v2
	v_mov_b32_e32 v15, v2
	v_mov_b32_e32 v16, v2
	v_mov_b32_e32 v17, v2
	v_mov_b32_e32 v18, v2
	v_mov_b32_e32 v19, v2
	v_mov_b32_e32 v20, v2
	v_mov_b32_e32 v21, v2
	v_mov_b32_e32 v22, v2
	v_mov_b32_e32 v23, v2
	v_mov_b32_e32 v24, v2
	v_mov_b32_e32 v25, v2
	v_mov_b32_e32 v26, v2
	v_mov_b32_e32 v27, v2
	v_mov_b32_e32 v28, v2
	v_mov_b32_e32 v29, v2
	v_mov_b32_e32 v30, v2
	v_mov_b32_e32 v31, v2
	v_mov_b32_e32 v32, v2
	v_mov_b32_e32 v33, v2
	v_mov_b32_e32 v34, v2
	v_mov_b32_e32 v35, v2
	v_mov_b32_e32 v36, v2
	v_mov_b32_e32 v37, v2
	v_mov_b32_e32 v38, v2
	v_mov_b32_e32 v39, v2
	v_mov_b32_e32 v40, v2
	v_mov_b32_e32 v41, v2
	v_mov_b32_e32 v42, v2
	v_mov_b32_e32 v43, v2
	v_mov_b32_e32 v44, v2
	v_mov_b32_e32 v45, v2
	v_mov_b32_e32 v46, v2
	v_mov_b32_e32 v47, v2
	v_mov_b32_e32 v48, v2
	v_mov_b32_e32 v49, v2
	v_mov_b32_e32 v50, v2
	v_mov_b32_e32 v51, v2
	v_mov_b32_e32 v52, v2
	v_mov_b32_e32 v53, v2
	v_mov_b32_e32 v54, v2
	v_mov_b32_e32 v55, v2
	v_mov_b32_e32 v56, v2
	v_mov_b32_e32 v57, v2
	v_mov_b32_e32 v58, v2
	v_mov_b32_e32 v59, v2
	v_mov_b32_e32 v60, v2
	v_mov_b32_e32 v61, v2
	v_mov_b32_e32 v62, v2
	v_mov_b32_e32 v63, v2
	v_mov_b32_e32 v64, v2
	v_mov_b32_e32 v65, v2
	v_mov_b32_e32 v66, v2
	v_mov_b32_e32 v67, v2
	v_mov_b32_e32 v68, v2
	v_mov_b32_e32 v69, v2
	v_mov_b32_e32 v70, v2
	v_mov_b32_e32 v71, v2
	v_mov_b32_e32 v72, v2
	v_mov_b32_e32 v73, v2
	v_mov_b32_e32 v74, v2
	v_mov_b32_e32 v75, v2
	v_mov_b32_e32 v76, v2
	v_mov_b32_e32 v77, v2
	v_mov_b32_e32 v78, v2
	v_mov_b32_e32 v79, v2
	v_mov_b32_e32 v80, v2
	v_mov_b32_e32 v81, v2
	v_mov_b32_e32 v82, v2
	v_mov_b32_e32 v83, v2
	v_mov_b32_e32 v84, v2
	v_mov_b32_e32 v85, v2
	v_mov_b32_e32 v86, v2
	v_mov_b32_e32 v87, v2
	v_mov_b32_e32 v88, v2
	v_mov_b32_e32 v89, v2
	v_mov_b32_e32 v90, v2
	v_mov_b32_e32 v91, v2
	v_mov_b32_e32 v92, v2
	v_mov_b32_e32 v93, v2
	v_mov_b32_e32 v94, v2
	v_mov_b32_e32 v95, v2
	v_mov_b32_e32 v96, v2
	v_mov_b32_e32 v97, v2
	s_mov_b32 s37, 0
	s_mov_b32 s23, 0
	v_add_u32_e32 v109, s23, v108
	v_add_u32_e32 v0, s23, v107
	v_add_u32_e32 v109, 0x3000, v109
	s_branch .LoA_head

; #define G3_TILE(kt_, st_) do { const size_t ko_ = (size_t)(kt_) * 1024; unsigned char* d_ = smem + (st_) * 20480; \
;         _Pragma("unroll") for (int s_ = 0; s_ < 12; ++s_) GLDS16(Abase + (size_t)s_ * ksub + ko_ + voff, d_ + s_ * 1024); \
;         _Pragma("unroll") for (int s_ = 0; s_ < 8; ++s_) GLDS16(Bbase + (size_t)s_ * ksub + ko_ + voff, d_ + 12288 + s_ * 1024); } while (0)
; template <int EPI>
; __device__ __forceinline__ void gemm_tile3(const Params& p, int l, const u16* __restrict__ A, int lda, const u16* __restrict__ Bt, int K, int m0, int n0, unsigned char* smem) {
;     ...
;     for (int kt = 0; kt < nk; ++kt) {
;         if (((kt + 1) & 3) == wid && kt + 1 < nk) asm volatile("s_waitcnt vmcnt(0)" ::: "memory");
;         __builtin_amdgcn_s_barrier();
;         asm volatile("" ::: "memory");
;         if (((kt + 3) & 3) == wid && kt + 3 < nk) G3_TILE(kt + 3, stn);
;         const int so = st * 20480;
.LoA_head:
	s_cmp_lt_u32 s37, 31
	s_cbranch_scc0 .LoA_wt
	s_waitcnt vmcnt(5)
.LoA_bar:
	s_barrier
	ds_read_b128 v[110:113], v109 offset:0
	ds_read_b128 v[114:117], v109 offset:1024
	ds_read_b128 v[118:121], v109 offset:2048
	ds_read_b128 v[122:125], v109 offset:3072
	ds_read_b128 v[126:129], v0 offset:0
	ds_read_b128 v[130:133], v0 offset:1024
	ds_read_b128 v[134:137], v0 offset:2048
	ds_read_b128 v[138:141], v0 offset:3072
	ds_read_b128 v[142:145], v0 offset:4096
	ds_read_b128 v[146:149], v0 offset:5120
	s_cmp_lt_u32 s37, 30
	s_cbranch_scc0 .LoA_mm
	s_add_i32 s17, s16, s54
	s_add_i32 s18, s16, s55
	s_mov_b32 m0, s17
	s_add_i32 s17, s17, 0x400
	global_load_lds_dwordx4 v252, s[28:29]
	s_mov_b32 m0, s17
	s_add_i32 s17, s17, 0x400
	global_load_lds_dwordx4 v253, s[28:29]
	s_mov_b32 m0, s17
	s_nop 0
	global_load_lds_dwordx4 v254, s[28:29]
	s_mov_b32 m0, s18
	s_add_i32 s18, s18, 0x400
	global_load_lds_dwordx4 v252, s[30:31]
	s_mov_b32 m0, s18
	s_add_u32 s28, s28, 0x400
	global_load_lds_dwordx4 v253, s[30:31]
	s_addc_u32 s29, s29, 0
	s_add_u32 s30, s30, 0x400
	s_addc_u32 s31, s31, 0
	s_add_i32 s16, s16, 0x5000
	s_cmp_eq_u32 s16, 0x14000
	s_cselect_b32 s16, 0, s16

; #define G3_TILE(kt_, st_) do { const size_t ko_ = (size_t)(kt_) * 1024; unsigned char* d_ = smem + (st_) * 20480; \
;         _Pragma("unroll") for (int s_ = 0; s_ < 12; ++s_) GLDS16(Abase + (size_t)s_ * ksub + ko_ + voff, d_ + s_ * 1024); \
;         _Pragma("unroll") for (int s_ = 0; s_ < 8; ++s_) GLDS16(Bbase + (size_t)s_ * ksub + ko_ + voff, d_ + 12288 + s_ * 1024); } while (0)
; template <int EPI>
; __device__ __forceinline__ void gemm_tile3(const Params& p, int l, const u16* __restrict__ A, int lda, const u16* __restrict__ Bt, int K, int m0, int n0, unsigned char* smem) {
;     ...
;     const int nk = K >> 5;
;     if (wid < 3) G3_TILE(wid, wid);
;     const unsigned char* fa = smem + (wr * 6) * 1024 + fr * 64 + fq * 16;
;     const unsigned char* fb = smem + 12288 + (wc * 4) * 1024 + fr * 64 + fq * 16;
;     int st = 0, stn = 3;
.Lf2_pro:
	s_add_i32 s17, s23, s54
	s_add_i32 s18, s23, s55
	s_mov_b32 m0, s17
	s_add_i32 s17, s17, 0x400
	global_load_lds_dwordx4 v252, s[28:29]
	s_mov_b32 m0, s17
	s_add_i32 s17, s17, 0x400
	global_load_lds_dwordx4 v253, s[28:29]
	s_mov_b32 m0, s17
	s_nop 0
	global_load_lds_dwordx4 v254, s[28:29]
	s_mov_b32 m0, s18
	s_add_i32 s18, s18, 0x400
	global_load_lds_dwordx4 v252, s[30:31]
	s_mov_b32 m0, s18
	s_add_u32 s28, s28, 0x400
	global_load_lds_dwordx4 v253, s[30:31]
	s_addc_u32 s29, s29, 0
	s_add_u32 s30, s30, 0x400
	s_addc_u32 s31, s31, 0
	s_add_i32 s23, s23, 0x5000
	s_cmp_lg_u32 s23, 0xa000
	s_cbranch_scc1 .Lf2_pro
	v_ashrrev_i32_e32 v105, 7, v104
	s_movk_i32 s17, 0x1800
	v_and_b32_e32 v106, 15, v104
	v_mul_lo_u32 v2, v105, s17
	v_and_b32_e32 v99, 1, v98
	v_lshlrev_b32_e32 v3, 6, v106
	v_and_b32_e32 v4, 48, v104
	v_and_b32_e32 v5, 8, v104
	v_lshlrev_b32_e32 v5, 2, v5
	v_xor_b32_e32 v4, v4, v5
	v_add3_u32 v107, v2, v3, v4
	v_lshlrev_b32_e32 v2, 12, v99
	v_add3_u32 v108, v2, v3, v4
	s_waitcnt lgkmcnt(0)
	v_mov_b32_e32 v2, 0
	v_mov_b32_e32 v3, v2
	v_mov_b32_e32 v4, v2
	v_mov_b32_e32 v5, v2
	v_mov_b32_e32 v6, v2
	v_mov_b32_e32 v7, v2
	v_mov_b32_e32 v8, v2
	v_mov_b32_e32 v9, v2
	v_mov_b32_e32 v10, v2
	v_mov_b32_e32 v11, v2
	v_mov_b32_e32 v12, v2
	v_mov_b32_e32 v13, v2
	v_mov_b32_e32 v14, v2
	v_mov_b32_e32 v15, v2
	v_mov_b32_e32 v16, v2
	v_mov_b32_e32 v17, v2
	v_mov_b32_e32 v18, v2
	v_mov_b32_e32 v19, v2
	v_mov_b32_e32 v20, v2
	v_mov_b32_e32 v21, v2
	v_mov_b32_e32 v22, v2
	v_mov_b32_e32 v23, v2
	v_mov_b32_e32 v24, v2
	v_mov_b32_e32 v25, v2
	v_mov_b32_e32 v26, v2
	v_mov_b32_e32 v27, v2
	v_mov_b32_e32 v28, v2
	v_mov_b32_e32 v29, v2
	v_mov_b32_e32 v30, v2
	v_mov_b32_e32 v31, v2
	v_mov_b32_e32 v32, v2
	v_mov_b32_e32 v33, v2
	v_mov_b32_e32 v34, v2
	v_mov_b32_e32 v35, v2
	v_mov_b32_e32 v36, v2
	v_mov_b32_e32 v37, v2
	v_mov_b32_e32 v38, v2
	v_mov_b32_e32 v39, v2
	v_mov_b32_e32 v40, v2
	v_mov_b32_e32 v41, v2
	v_mov_b32_e32 v42, v2
	v_mov_b32_e32 v43, v2
	v_mov_b32_e32 v44, v2
	v_mov_b32_e32 v45, v2
	v_mov_b32_e32 v46, v2
	v_mov_b32_e32 v47, v2
	v_mov_b32_e32 v48, v2
	v_mov_b32_e32 v49, v2
	v_mov_b32_e32 v50, v2
	v_mov_b32_e32 v51, v2
	v_mov_b32_e32 v52, v2
	v_mov_b32_e32 v53, v2
	v_mov_b32_e32 v54, v2
	v_mov_b32_e32 v55, v2
	v_mov_b32_e32 v56, v2
	v_mov_b32_e32 v57, v2
	v_mov_b32_e32 v58, v2
	v_mov_b32_e32 v59, v2
	v_mov_b32_e32 v60, v2
	v_mov_b32_e32 v61, v2
	v_mov_b32_e32 v62, v2
	v_mov_b32_e32 v63, v2
	v_mov_b32_e32 v64, v2
	v_mov_b32_e32 v65, v2
	v_mov_b32_e32 v66, v2
	v_mov_b32_e32 v67, v2
	v_mov_b32_e32 v68, v2
	v_mov_b32_e32 v69, v2
	v_mov_b32_e32 v70, v2
	v_mov_b32_e32 v71, v2
	v_mov_b32_e32 v72, v2
	v_mov_b32_e32 v73, v2
	v_mov_b32_e32 v74, v2
	v_mov_b32_e32 v75, v2
	v_mov_b32_e32 v76, v2
	v_mov_b32_e32 v77, v2
	v_mov_b32_e32 v78, v2
	v_mov_b32_e32 v79, v2
	v_mov_b32_e32 v80, v2
	v_mov_b32_e32 v81, v2
	v_mov_b32_e32 v82, v2
	v_mov_b32_e32 v83, v2
	v_mov_b32_e32 v84, v2
	v_mov_b32_e32 v85, v2
	v_mov_b32_e32 v86, v2
	v_mov_b32_e32 v87, v2
	v_mov_b32_e32 v88, v2
	v_mov_b32_e32 v89, v2
	v_mov_b32_e32 v90, v2
	v_mov_b32_e32 v91, v2
	v_mov_b32_e32 v92, v2
	v_mov_b32_e32 v93, v2
	v_mov_b32_e32 v94, v2
	v_mov_b32_e32 v95, v2
	v_mov_b32_e32 v96, v2
	v_mov_b32_e32 v97, v2
	s_mov_b32 s50, 0
	s_mov_b32 s41, 0
	v_add_u32_e32 v109, s41, v108
	v_add_u32_e32 v0, s41, v107
	v_add_u32_e32 v109, 0x3000, v109
	s_branch .Lf2_head

; #define G3_TILE(kt_, st_) do { const size_t ko_ = (size_t)(kt_) * 1024; unsigned char* d_ = smem + (st_) * 20480; \
;         _Pragma("unroll") for (int s_ = 0; s_ < 12; ++s_) GLDS16(Abase + (size_t)s_ * ksub + ko_ + voff, d_ + s_ * 1024); \
;         _Pragma("unroll") for (int s_ = 0; s_ < 8; ++s_) GLDS16(Bbase + (size_t)s_ * ksub + ko_ + voff, d_ + 12288 + s_ * 1024); } while (0)
; template <int EPI>
; __device__ __forceinline__ void gemm_tile3(const Params& p, int l, const u16* __restrict__ A, int lda, const u16* __restrict__ Bt, int K, int m0, int n0, unsigned char* smem) {
;     ...
;     for (int kt = 0; kt < nk; ++kt) {
;         if (((kt + 1) & 3) == wid && kt + 1 < nk) asm volatile("s_waitcnt vmcnt(0)" ::: "memory");
;         __builtin_amdgcn_s_barrier();
;         asm volatile("" ::: "memory");
;         if (((kt + 3) & 3) == wid && kt + 3 < nk) G3_TILE(kt + 3, stn);
;         const int so = st * 20480;
.Lf2_head:
	s_cmp_lt_u32 s50, 87
	s_cbranch_scc0 .Lf2_wt
	s_waitcnt vmcnt(5)
.Lf2_bar:
	s_barrier
	ds_read_b128 v[110:113], v109 offset:0
	ds_read_b128 v[114:117], v109 offset:1024
	ds_read_b128 v[118:121], v109 offset:2048
	ds_read_b128 v[122:125], v109 offset:3072
	ds_read_b128 v[126:129], v0 offset:0
	ds_read_b128 v[130:133], v0 offset:1024
	ds_read_b128 v[134:137], v0 offset:2048
	ds_read_b128 v[138:141], v0 offset:3072
	ds_read_b128 v[142:145], v0 offset:4096
	ds_read_b128 v[146:149], v0 offset:5120
	s_cmp_lt_u32 s50, 86
	s_cbranch_scc0 .Lf2_mm
	s_add_i32 s17, s23, s54
	s_add_i32 s18, s23, s55
	s_mov_b32 m0, s17
	s_add_i32 s17, s17, 0x400
	global_load_lds_dwordx4 v252, s[28:29]
	s_mov_b32 m0, s17
	s_add_i32 s17, s17, 0x400
	global_load_lds_dwordx4 v253, s[28:29]
	s_mov_b32 m0, s17
	s_nop 0
	global_load_lds_dwordx4 v254, s[28:29]
	s_mov_b32 m0, s18
	s_add_i32 s18, s18, 0x400
	global_load_lds_dwordx4 v252, s[30:31]
	s_mov_b32 m0, s18
	s_add_u32 s28, s28, 0x400
	global_load_lds_dwordx4 v253, s[30:31]
	s_addc_u32 s29, s29, 0
	s_add_u32 s30, s30, 0x400
	s_addc_u32 s31, s31, 0
	s_add_i32 s23, s23, 0x5000
	s_cmp_eq_u32 s23, 0x14000
	s_cselect_b32 s23, 0, s23
